# DF unit-end wait relaxed to lgkmcnt only (u stores drain behind next unit prologue)
# baseline (speedup 1.0000x reference)
.LBB0_299:
	s_waitcnt lgkmcnt(0)
	s_barrier
